# attention main loop: exp/pack/PV section hand-scheduled, three of four exp groups issued in the shadow of the previous group's PV MFMAs (MFMA-VALU interleave)
# speedup vs baseline: 1.0130x; 1.0130x over previous
; #define LAS __attribute__((address_space(3)))
; __device__ __forceinline__ unsigned cvtpk(float lo, float hi) { f32x2_t v = {lo, hi}; bf16x2_t b = __builtin_convertvector(v, bf16x2_t); return __builtin_bit_cast(unsigned, b); }
; __device__ __forceinline__ void unit(unsigned char* ws, LAS unsigned char* lds, int b, int h, int mp, int qb, const int tid_in) {
;     ...
;             for (int jt = 0; jt < 4; ++jt) {
; #pragma unroll
;                 for (int jj = 0; jj < 4; ++jj) s[g][jt][jj] = __builtin_amdgcn_exp2f(s[g][jt][jj]); }
; #pragma unroll
;             for (int sb = 0; sb < 2; ++sb) { u32x4 pw; pw.x = cvtpk(s[g][2 * sb][0], s[g][2 * sb][1]); pw.y = cvtpk(s[g][2 * sb][2], s[g][2 * sb][3]); pw.z = cvtpk(s[g][2 * sb + 1][0], s[g][2 * sb + 1][1]); pw.w = cvtpk(s[g][2 * sb + 1][2], s[g][2 * sb + 1][3]);
;                 pf[g][sb] = __builtin_bit_cast(bf16x8, pw); }
;         }
; #pragma unroll
;         for (int g = 0; g < 2; ++g) {
;             lacc[g] = __builtin_amdgcn_mfma_f32_16x16x32_bf16(onesf, pf[g][0], lacc[g], 0, 0, 0); lacc[g] = __builtin_amdgcn_mfma_f32_16x16x32_bf16(onesf, pf[g][1], lacc[g], 0, 0, 0); }
; #pragma unroll
;         for (int et = 0; et < 8; ++et) { const LAS bf16_t* vrow = VT + (16 * et + fr) * KP;
;             const bf16x8 vf0 = *(const LAS bf16x8*)(vrow + ((8 * fq + 8 * et) & 63)), vf1 = *(const LAS bf16x8*)(vrow + ((32 + 8 * fq + 8 * et) & 63));
; #pragma unroll
;             for (int g = 0; g < 2; ++g) { o[g][et] = __builtin_amdgcn_mfma_f32_16x16x32_bf16(vf0, pf[g][0], o[g][et], 0, 0, 0); o[g][et] = __builtin_amdgcn_mfma_f32_16x16x32_bf16(vf1, pf[g][1], o[g][et], 0, 0, 0); } }
.LBB0_195:
	v_lshl_add_u32 v210, v168, 1, v179
	v_lshl_add_u32 v211, v167, 1, v179
	v_lshl_add_u32 v212, v166, 1, v179
	v_mov_b32_e32 v206, s20
	v_mov_b32_e32 v207, s20
	v_mov_b32_e32 v208, s20
	v_mov_b32_e32 v209, s20
	ds_read_b128 v[222:225], v178 offset:9216
	ds_read_b128 v[226:229], v178 offset:11536
	ds_read_b128 v[230:233], v178 offset:13856
	ds_read_b128 v[234:237], v178 offset:16176
	ds_read_b128 v[238:241], v178 offset:18496
	ds_read_b128 v[242:245], v210 offset:20736
	ds_read_b128 v[246:249], v211 offset:23040
	ds_read_b128 v[250:253], v212 offset:25344
	v_exp_f32_e32 v126, v126
	v_exp_f32_e32 v127, v127
	v_exp_f32_e32 v128, v128
	v_exp_f32_e32 v129, v129
	v_exp_f32_e32 v130, v130
	v_exp_f32_e32 v131, v131
	v_exp_f32_e32 v132, v132
	v_exp_f32_e32 v133, v133
	v_cvt_pk_bf16_f32 v126, v126, v127
	v_cvt_pk_bf16_f32 v127, v128, v129
	v_cvt_pk_bf16_f32 v128, v130, v131
	v_cvt_pk_bf16_f32 v129, v132, v133
	s_nop 1
	s_waitcnt lgkmcnt(7)
	v_mfma_f32_16x16x32_bf16 v[70:73], v[206:209], v[126:129], v[70:73]
	v_exp_f32_e32 v114, v114
	s_waitcnt lgkmcnt(7)
	v_mfma_f32_16x16x32_bf16 v[66:69], v[222:225], v[126:129], v[66:69]
	v_exp_f32_e32 v115, v115
	s_waitcnt lgkmcnt(6)
	v_mfma_f32_16x16x32_bf16 v[62:65], v[226:229], v[126:129], v[62:65]
	v_exp_f32_e32 v116, v116
	s_waitcnt lgkmcnt(5)
	v_mfma_f32_16x16x32_bf16 v[58:61], v[230:233], v[126:129], v[58:61]
	v_exp_f32_e32 v117, v117
	s_waitcnt lgkmcnt(4)
	v_mfma_f32_16x16x32_bf16 v[54:57], v[234:237], v[126:129], v[54:57]
	v_exp_f32_e32 v118, v118
	s_waitcnt lgkmcnt(3)
	v_mfma_f32_16x16x32_bf16 v[50:53], v[238:241], v[126:129], v[50:53]
	v_exp_f32_e32 v119, v119
	v_cvt_pk_bf16_f32 v114, v114, v115
	s_waitcnt lgkmcnt(2)
	v_mfma_f32_16x16x32_bf16 v[46:49], v[242:245], v[126:129], v[46:49]
	v_exp_f32_e32 v120, v120
	v_cvt_pk_bf16_f32 v115, v116, v117
	s_waitcnt lgkmcnt(1)
	v_mfma_f32_16x16x32_bf16 v[42:45], v[246:249], v[126:129], v[42:45]
	v_exp_f32_e32 v121, v121
	v_cvt_pk_bf16_f32 v116, v118, v119
	s_waitcnt lgkmcnt(0)
	v_mfma_f32_16x16x32_bf16 v[34:37], v[250:253], v[126:129], v[34:37]
	v_cvt_pk_bf16_f32 v117, v120, v121
	s_nop 1
	v_mfma_f32_16x16x32_bf16 v[38:41], v[206:209], v[114:117], v[38:41]
	v_exp_f32_e32 v138, v138
	v_mfma_f32_16x16x32_bf16 v[30:33], v[222:225], v[114:117], v[30:33]
	ds_read_b128 v[222:225], v178 offset:9280
	v_exp_f32_e32 v139, v139
	v_mfma_f32_16x16x32_bf16 v[26:29], v[226:229], v[114:117], v[26:29]
	ds_read_b128 v[226:229], v210 offset:11520
	v_exp_f32_e32 v140, v140
	v_mfma_f32_16x16x32_bf16 v[22:25], v[230:233], v[114:117], v[22:25]
	ds_read_b128 v[230:233], v211 offset:13824
	v_exp_f32_e32 v141, v141
	v_mfma_f32_16x16x32_bf16 v[10:13], v[234:237], v[114:117], v[10:13]
	ds_read_b128 v[234:237], v212 offset:16128
	v_exp_f32_e32 v142, v142
	v_mfma_f32_16x16x32_bf16 v[18:21], v[238:241], v[114:117], v[18:21]
	ds_read_b128 v[238:241], v178 offset:18432
	v_exp_f32_e32 v143, v143
	v_cvt_pk_bf16_f32 v130, v138, v139
	v_mfma_f32_16x16x32_bf16 v[14:17], v[242:245], v[114:117], v[14:17]
	ds_read_b128 v[242:245], v178 offset:20752
	v_exp_f32_e32 v144, v144
	v_cvt_pk_bf16_f32 v131, v140, v141
	v_mfma_f32_16x16x32_bf16 v[6:9], v[246:249], v[114:117], v[6:9]
	ds_read_b128 v[246:249], v178 offset:23072
	v_exp_f32_e32 v145, v145
	v_cvt_pk_bf16_f32 v132, v142, v143
	v_mfma_f32_16x16x32_bf16 v[2:5], v[250:253], v[114:117], v[2:5]
	ds_read_b128 v[250:253], v178 offset:25392
	v_cvt_pk_bf16_f32 v133, v144, v145
	s_nop 1
	v_mfma_f32_16x16x32_bf16 v[70:73], v[206:209], v[130:133], v[70:73]
	v_exp_f32_e32 v122, v122
	s_waitcnt lgkmcnt(7)
	v_mfma_f32_16x16x32_bf16 v[66:69], v[222:225], v[130:133], v[66:69]
	v_exp_f32_e32 v123, v123
	s_waitcnt lgkmcnt(6)
	v_mfma_f32_16x16x32_bf16 v[62:65], v[226:229], v[130:133], v[62:65]
	v_exp_f32_e32 v124, v124
	s_waitcnt lgkmcnt(5)
	v_mfma_f32_16x16x32_bf16 v[58:61], v[230:233], v[130:133], v[58:61]
	v_exp_f32_e32 v125, v125
	s_waitcnt lgkmcnt(4)
	v_mfma_f32_16x16x32_bf16 v[54:57], v[234:237], v[130:133], v[54:57]
	v_exp_f32_e32 v134, v134
	s_waitcnt lgkmcnt(3)
	v_mfma_f32_16x16x32_bf16 v[50:53], v[238:241], v[130:133], v[50:53]
	v_exp_f32_e32 v135, v135
	v_cvt_pk_bf16_f32 v118, v122, v123
	s_waitcnt lgkmcnt(2)
	v_mfma_f32_16x16x32_bf16 v[46:49], v[242:245], v[130:133], v[46:49]
	v_exp_f32_e32 v136, v136
	v_cvt_pk_bf16_f32 v119, v124, v125
	s_waitcnt lgkmcnt(1)
	v_mfma_f32_16x16x32_bf16 v[42:45], v[246:249], v[130:133], v[42:45]
	v_exp_f32_e32 v137, v137
	v_cvt_pk_bf16_f32 v120, v134, v135
	s_waitcnt lgkmcnt(0)
	v_mfma_f32_16x16x32_bf16 v[34:37], v[250:253], v[130:133], v[34:37]
	v_cvt_pk_bf16_f32 v121, v136, v137
	s_nop 1
	v_mfma_f32_16x16x32_bf16 v[38:41], v[206:209], v[118:121], v[38:41]
	v_mfma_f32_16x16x32_bf16 v[30:33], v[222:225], v[118:121], v[30:33]
	v_mfma_f32_16x16x32_bf16 v[26:29], v[226:229], v[118:121], v[26:29]
	v_mfma_f32_16x16x32_bf16 v[22:25], v[230:233], v[118:121], v[22:25]
	v_mfma_f32_16x16x32_bf16 v[10:13], v[234:237], v[118:121], v[10:13]
	v_mfma_f32_16x16x32_bf16 v[18:21], v[238:241], v[118:121], v[18:21]
	v_mfma_f32_16x16x32_bf16 v[14:17], v[242:245], v[118:121], v[14:17]
	v_mfma_f32_16x16x32_bf16 v[6:9], v[246:249], v[118:121], v[6:9]
	v_mfma_f32_16x16x32_bf16 v[2:5], v[250:253], v[118:121], v[2:5]
